# phase-0 GEMV k-loop unrolled x4 and software-pipelined: each iteration's 16 strided weight loads issued one iteration ahead into a second register set
# baseline (speedup 1.0000x reference)
.LBB0_105:
	s_mov_b64 s[38:39], 0x6000
	s_mov_b64 s[12:13], 0x0
	v_lshl_add_u64 v[232:233], v[76:77], 0, s[12:13]
	global_load_dword v110, v[232:233], off
	v_lshl_add_u64 v[232:233], v[232:233], 0, s[38:39]
	global_load_dword v112, v[232:233], off
	v_lshl_add_u64 v[232:233], v[232:233], 0, s[38:39]
	global_load_dword v114, v[232:233], off
	v_lshl_add_u64 v[232:233], v[232:233], 0, s[38:39]
	global_load_dword v116, v[232:233], off
	v_lshl_add_u64 v[232:233], v[232:233], 0, s[38:39]
	global_load_dword v118, v[232:233], off
	v_lshl_add_u64 v[232:233], v[232:233], 0, s[38:39]
	global_load_dword v120, v[232:233], off
	v_lshl_add_u64 v[232:233], v[232:233], 0, s[38:39]
	global_load_dword v122, v[232:233], off
	v_lshl_add_u64 v[232:233], v[232:233], 0, s[38:39]
	global_load_dword v124, v[232:233], off
	v_lshl_add_u64 v[232:233], v[232:233], 0, s[38:39]
	global_load_dword v126, v[232:233], off
	v_lshl_add_u64 v[232:233], v[232:233], 0, s[38:39]
	global_load_dword v128, v[232:233], off
	v_lshl_add_u64 v[232:233], v[232:233], 0, s[38:39]
	global_load_dword v130, v[232:233], off
	v_lshl_add_u64 v[232:233], v[232:233], 0, s[38:39]
	global_load_dword v132, v[232:233], off
	v_lshl_add_u64 v[232:233], v[232:233], 0, s[38:39]
	global_load_dword v134, v[232:233], off
	v_lshl_add_u64 v[232:233], v[232:233], 0, s[38:39]
	global_load_dword v136, v[232:233], off
	v_lshl_add_u64 v[232:233], v[232:233], 0, s[38:39]
	global_load_dword v138, v[232:233], off
	v_lshl_add_u64 v[232:233], v[232:233], 0, s[38:39]
	global_load_dword v82, v[232:233], off
	s_mov_b64 s[12:13], 0x60000
	v_lshl_add_u64 v[232:233], v[76:77], 0, s[12:13]
	global_load_dword v200, v[232:233], off
	v_lshl_add_u64 v[232:233], v[232:233], 0, s[38:39]
	global_load_dword v202, v[232:233], off
	v_lshl_add_u64 v[232:233], v[232:233], 0, s[38:39]
	global_load_dword v204, v[232:233], off
	v_lshl_add_u64 v[232:233], v[232:233], 0, s[38:39]
	global_load_dword v206, v[232:233], off
	v_lshl_add_u64 v[232:233], v[232:233], 0, s[38:39]
	global_load_dword v208, v[232:233], off
	v_lshl_add_u64 v[232:233], v[232:233], 0, s[38:39]
	global_load_dword v210, v[232:233], off
	v_lshl_add_u64 v[232:233], v[232:233], 0, s[38:39]
	global_load_dword v212, v[232:233], off
	v_lshl_add_u64 v[232:233], v[232:233], 0, s[38:39]
	global_load_dword v214, v[232:233], off
	v_lshl_add_u64 v[232:233], v[232:233], 0, s[38:39]
	global_load_dword v216, v[232:233], off
	v_lshl_add_u64 v[232:233], v[232:233], 0, s[38:39]
	global_load_dword v218, v[232:233], off
	v_lshl_add_u64 v[232:233], v[232:233], 0, s[38:39]
	global_load_dword v220, v[232:233], off
	v_lshl_add_u64 v[232:233], v[232:233], 0, s[38:39]
	global_load_dword v222, v[232:233], off
	v_lshl_add_u64 v[232:233], v[232:233], 0, s[38:39]
	global_load_dword v224, v[232:233], off
	v_lshl_add_u64 v[232:233], v[232:233], 0, s[38:39]
	global_load_dword v226, v[232:233], off
	v_lshl_add_u64 v[232:233], v[232:233], 0, s[38:39]
	global_load_dword v228, v[232:233], off
	v_lshl_add_u64 v[232:233], v[232:233], 0, s[38:39]
	global_load_dword v230, v[232:233], off
	ds_read_b128 v[18:21], v62
	ds_read_b128 v[14:17], v62 offset:16
	ds_read_b128 v[10:13], v62 offset:32
	ds_read_b128 v[6:9], v62 offset:48
	ds_read_b128 v[2:5], v62 offset:4096
	ds_read_b128 v[22:25], v62 offset:4112
	ds_read_b128 v[38:41], v62 offset:8192
	ds_read_b128 v[34:37], v62 offset:8208
	ds_read_b128 v[30:33], v62 offset:12288
	ds_read_b128 v[26:29], v62 offset:12304
	ds_read_b128 v[46:49], v62 offset:16384
	ds_read_b128 v[42:45], v62 offset:16400
	ds_read_b128 v[50:53], v62 offset:4128
	ds_read_b128 v[54:57], v62 offset:4144
	ds_read_b128 v[90:93], v62 offset:8224
	ds_read_b128 v[94:97], v62 offset:8240
	ds_read_b128 v[98:101], v62 offset:12320
	ds_read_b128 v[58:61], v62 offset:12336
	ds_read_b128 v[102:105], v62 offset:16416
	ds_read_b128 v[106:109], v62 offset:16432
	s_waitcnt lgkmcnt(14)
	v_mov_b32_e32 v140, v18
	v_mov_b32_e32 v141, v2
	v_mov_b32_e32 v2, v19
	v_mov_b32_e32 v18, v20
	v_mov_b32_e32 v19, v4
	v_mov_b32_e32 v4, v21
	s_waitcnt lgkmcnt(13)
	v_mov_b32_e32 v20, v38
	s_waitcnt lgkmcnt(11)
	v_mov_b32_e32 v21, v30
	v_mov_b32_e32 v30, v39
	v_mov_b32_e32 v38, v40
	v_mov_b32_e32 v39, v32
	v_mov_b32_e32 v32, v41
	v_mov_b32_e32 v40, v14
	v_mov_b32_e32 v41, v22
	v_mov_b32_e32 v22, v15
	v_mov_b32_e32 v14, v16
	v_mov_b32_e32 v15, v24
	v_mov_b32_e32 v24, v17
	v_mov_b32_e32 v16, v34
	s_waitcnt lgkmcnt(10)
	v_mov_b32_e32 v17, v26
	v_mov_b32_e32 v26, v35
	v_mov_b32_e32 v34, v36
	v_mov_b32_e32 v35, v28
	v_mov_b32_e32 v28, v37
	v_mov_b32_e32 v36, v10
	s_waitcnt lgkmcnt(7)
	v_mov_b32_e32 v37, v50
	v_mov_b32_e32 v50, v11
	v_mov_b32_e32 v10, v12
	v_mov_b32_e32 v11, v52
	v_mov_b32_e32 v52, v13
	s_waitcnt lgkmcnt(5)
	v_mov_b32_e32 v12, v90
	s_waitcnt lgkmcnt(3)
	v_mov_b32_e32 v13, v98
	v_mov_b32_e32 v98, v91
	v_mov_b32_e32 v90, v92
	v_mov_b32_e32 v91, v100
	v_mov_b32_e32 v100, v93
	v_mov_b32_e32 v92, v6
	v_mov_b32_e32 v93, v54
	s_waitcnt vmcnt(31)
	v_pk_fma_f32 v[78:79], v[110:111], v[140:141], v[78:79] op_sel_hi:[0,1,1]
	v_pk_fma_f32 v[20:21], v[110:111], v[20:21], v[80:81] op_sel_hi:[0,1,1]
	v_fmac_f32_e32 v71, v110, v46
	v_mov_b32_e32 v54, v7
	v_mov_b32_e32 v6, v8
	v_mov_b32_e32 v7, v56
	v_mov_b32_e32 v56, v9
	v_mov_b32_e32 v8, v94
	s_waitcnt lgkmcnt(2)
	v_mov_b32_e32 v9, v58
	v_mov_b32_e32 v58, v95
	v_mov_b32_e32 v94, v96
	v_mov_b32_e32 v95, v60
	v_mov_b32_e32 v60, v97
	s_waitcnt vmcnt(30)
	v_pk_fma_f32 v[2:3], v[112:113], v[2:3], v[78:79] op_sel_hi:[0,1,1]
	v_pk_fma_f32 v[20:21], v[112:113], v[30:31], v[20:21] op_sel_hi:[0,1,1]
	v_fmac_f32_e32 v71, v112, v47
	s_waitcnt vmcnt(29)
	v_pk_fma_f32 v[2:3], v[114:115], v[18:19], v[2:3] op_sel_hi:[0,1,1]
	v_pk_fma_f32 v[18:19], v[114:115], v[38:39], v[20:21] op_sel_hi:[0,1,1]
	v_fmac_f32_e32 v71, v114, v48
	s_waitcnt vmcnt(28)
	v_pk_fma_f32 v[2:3], v[116:117], v[4:5], v[2:3] op_sel_hi:[0,1,1]
	v_pk_fma_f32 v[4:5], v[116:117], v[32:33], v[18:19] op_sel_hi:[0,1,1]
	v_fmac_f32_e32 v71, v116, v49
	s_waitcnt vmcnt(27)
	v_pk_fma_f32 v[2:3], v[118:119], v[40:41], v[2:3] op_sel_hi:[0,1,1]
	v_pk_fma_f32 v[4:5], v[118:119], v[16:17], v[4:5] op_sel_hi:[0,1,1]
	v_fmac_f32_e32 v71, v118, v42
	s_waitcnt vmcnt(26)
	v_pk_fma_f32 v[2:3], v[120:121], v[22:23], v[2:3] op_sel_hi:[0,1,1]
	v_pk_fma_f32 v[4:5], v[120:121], v[26:27], v[4:5] op_sel_hi:[0,1,1]
	v_fmac_f32_e32 v71, v120, v43
	s_waitcnt vmcnt(25)
	v_pk_fma_f32 v[2:3], v[122:123], v[14:15], v[2:3] op_sel_hi:[0,1,1]
	v_pk_fma_f32 v[4:5], v[122:123], v[34:35], v[4:5] op_sel_hi:[0,1,1]
	v_fmac_f32_e32 v71, v122, v44
	s_waitcnt vmcnt(24)
	v_pk_fma_f32 v[2:3], v[124:125], v[24:25], v[2:3] op_sel_hi:[0,1,1]
	v_pk_fma_f32 v[4:5], v[124:125], v[28:29], v[4:5] op_sel_hi:[0,1,1]
	v_fmac_f32_e32 v71, v124, v45
	s_waitcnt vmcnt(23)
	v_pk_fma_f32 v[2:3], v[126:127], v[36:37], v[2:3] op_sel_hi:[0,1,1]
	v_pk_fma_f32 v[4:5], v[126:127], v[12:13], v[4:5] op_sel_hi:[0,1,1]
	s_waitcnt lgkmcnt(1)
	v_fmac_f32_e32 v71, v126, v102
	s_waitcnt vmcnt(22)
	v_pk_fma_f32 v[2:3], v[128:129], v[50:51], v[2:3] op_sel_hi:[0,1,1]
	v_pk_fma_f32 v[4:5], v[128:129], v[98:99], v[4:5] op_sel_hi:[0,1,1]
	v_fmac_f32_e32 v71, v128, v103
	s_waitcnt vmcnt(21)
	v_pk_fma_f32 v[2:3], v[130:131], v[10:11], v[2:3] op_sel_hi:[0,1,1]
	v_pk_fma_f32 v[4:5], v[130:131], v[90:91], v[4:5] op_sel_hi:[0,1,1]
	v_fmac_f32_e32 v71, v130, v104
	s_waitcnt vmcnt(20)
	v_pk_fma_f32 v[2:3], v[132:133], v[52:53], v[2:3] op_sel_hi:[0,1,1]
	v_pk_fma_f32 v[4:5], v[132:133], v[100:101], v[4:5] op_sel_hi:[0,1,1]
	v_fmac_f32_e32 v71, v132, v105
	s_waitcnt vmcnt(19)
	v_pk_fma_f32 v[2:3], v[134:135], v[92:93], v[2:3] op_sel_hi:[0,1,1]
	v_pk_fma_f32 v[4:5], v[134:135], v[8:9], v[4:5] op_sel_hi:[0,1,1]
	s_waitcnt lgkmcnt(0)
	v_fmac_f32_e32 v71, v134, v106
	s_waitcnt vmcnt(18)
	v_pk_fma_f32 v[2:3], v[136:137], v[54:55], v[2:3] op_sel_hi:[0,1,1]
	v_pk_fma_f32 v[4:5], v[136:137], v[58:59], v[4:5] op_sel_hi:[0,1,1]
	v_fmac_f32_e32 v71, v136, v107
	s_waitcnt vmcnt(17)
	v_pk_fma_f32 v[2:3], v[138:139], v[6:7], v[2:3] op_sel_hi:[0,1,1]
	v_pk_fma_f32 v[4:5], v[138:139], v[94:95], v[4:5] op_sel_hi:[0,1,1]
	v_fmac_f32_e32 v71, v138, v108
	v_add_u32_e32 v62, 64, v62
	s_waitcnt vmcnt(16)
	v_pk_fma_f32 v[78:79], v[82:83], v[56:57], v[2:3] op_sel_hi:[0,1,1]
	v_pk_fma_f32 v[80:81], v[82:83], v[60:61], v[4:5] op_sel_hi:[0,1,1]
	v_fmac_f32_e32 v71, v82, v109
	s_mov_b64 s[12:13], 0xc0000
	v_lshl_add_u64 v[232:233], v[76:77], 0, s[12:13]
	global_load_dword v110, v[232:233], off
	v_lshl_add_u64 v[232:233], v[232:233], 0, s[38:39]
	global_load_dword v112, v[232:233], off
	v_lshl_add_u64 v[232:233], v[232:233], 0, s[38:39]
	global_load_dword v114, v[232:233], off
	v_lshl_add_u64 v[232:233], v[232:233], 0, s[38:39]
	global_load_dword v116, v[232:233], off
	v_lshl_add_u64 v[232:233], v[232:233], 0, s[38:39]
	global_load_dword v118, v[232:233], off
	v_lshl_add_u64 v[232:233], v[232:233], 0, s[38:39]
	global_load_dword v120, v[232:233], off
	v_lshl_add_u64 v[232:233], v[232:233], 0, s[38:39]
	global_load_dword v122, v[232:233], off
	v_lshl_add_u64 v[232:233], v[232:233], 0, s[38:39]
	global_load_dword v124, v[232:233], off
	v_lshl_add_u64 v[232:233], v[232:233], 0, s[38:39]
	global_load_dword v126, v[232:233], off
	v_lshl_add_u64 v[232:233], v[232:233], 0, s[38:39]
	global_load_dword v128, v[232:233], off
	v_lshl_add_u64 v[232:233], v[232:233], 0, s[38:39]
	global_load_dword v130, v[232:233], off
	v_lshl_add_u64 v[232:233], v[232:233], 0, s[38:39]
	global_load_dword v132, v[232:233], off
	v_lshl_add_u64 v[232:233], v[232:233], 0, s[38:39]
	global_load_dword v134, v[232:233], off
	v_lshl_add_u64 v[232:233], v[232:233], 0, s[38:39]
	global_load_dword v136, v[232:233], off
	v_lshl_add_u64 v[232:233], v[232:233], 0, s[38:39]
	global_load_dword v138, v[232:233], off
	v_lshl_add_u64 v[232:233], v[232:233], 0, s[38:39]
	global_load_dword v82, v[232:233], off
	ds_read_b128 v[18:21], v62
	ds_read_b128 v[14:17], v62 offset:16
	ds_read_b128 v[10:13], v62 offset:32
	ds_read_b128 v[6:9], v62 offset:48
	ds_read_b128 v[2:5], v62 offset:4096
	ds_read_b128 v[22:25], v62 offset:4112
	ds_read_b128 v[38:41], v62 offset:8192
	ds_read_b128 v[34:37], v62 offset:8208
	ds_read_b128 v[30:33], v62 offset:12288
	ds_read_b128 v[26:29], v62 offset:12304
	ds_read_b128 v[46:49], v62 offset:16384
	ds_read_b128 v[42:45], v62 offset:16400
	ds_read_b128 v[50:53], v62 offset:4128
	ds_read_b128 v[54:57], v62 offset:4144
	ds_read_b128 v[90:93], v62 offset:8224
	ds_read_b128 v[94:97], v62 offset:8240
	ds_read_b128 v[98:101], v62 offset:12320
	ds_read_b128 v[58:61], v62 offset:12336
	ds_read_b128 v[102:105], v62 offset:16416
	ds_read_b128 v[106:109], v62 offset:16432
	s_waitcnt lgkmcnt(14)
	v_mov_b32_e32 v140, v18
	v_mov_b32_e32 v141, v2
	v_mov_b32_e32 v2, v19
	v_mov_b32_e32 v18, v20
	v_mov_b32_e32 v19, v4
	v_mov_b32_e32 v4, v21
	s_waitcnt lgkmcnt(13)
	v_mov_b32_e32 v20, v38
	s_waitcnt lgkmcnt(11)
	v_mov_b32_e32 v21, v30
	v_mov_b32_e32 v30, v39
	v_mov_b32_e32 v38, v40
	v_mov_b32_e32 v39, v32
	v_mov_b32_e32 v32, v41
	v_mov_b32_e32 v40, v14
	v_mov_b32_e32 v41, v22
	v_mov_b32_e32 v22, v15
	v_mov_b32_e32 v14, v16
	v_mov_b32_e32 v15, v24
	v_mov_b32_e32 v24, v17
	v_mov_b32_e32 v16, v34
	s_waitcnt lgkmcnt(10)
	v_mov_b32_e32 v17, v26
	v_mov_b32_e32 v26, v35
	v_mov_b32_e32 v34, v36
	v_mov_b32_e32 v35, v28
	v_mov_b32_e32 v28, v37
	v_mov_b32_e32 v36, v10
	s_waitcnt lgkmcnt(7)
	v_mov_b32_e32 v37, v50
	v_mov_b32_e32 v50, v11
	v_mov_b32_e32 v10, v12
	v_mov_b32_e32 v11, v52
	v_mov_b32_e32 v52, v13
	s_waitcnt lgkmcnt(5)
	v_mov_b32_e32 v12, v90
	s_waitcnt lgkmcnt(3)
	v_mov_b32_e32 v13, v98
	v_mov_b32_e32 v98, v91
	v_mov_b32_e32 v90, v92
	v_mov_b32_e32 v91, v100
	v_mov_b32_e32 v100, v93
	v_mov_b32_e32 v92, v6
	v_mov_b32_e32 v93, v54
	s_waitcnt vmcnt(31)
	v_pk_fma_f32 v[78:79], v[200:201], v[140:141], v[78:79] op_sel_hi:[0,1,1]
	v_pk_fma_f32 v[20:21], v[200:201], v[20:21], v[80:81] op_sel_hi:[0,1,1]
	v_fmac_f32_e32 v71, v200, v46
	v_mov_b32_e32 v54, v7
	v_mov_b32_e32 v6, v8
	v_mov_b32_e32 v7, v56
	v_mov_b32_e32 v56, v9
	v_mov_b32_e32 v8, v94
	s_waitcnt lgkmcnt(2)
	v_mov_b32_e32 v9, v58
	v_mov_b32_e32 v58, v95
	v_mov_b32_e32 v94, v96
	v_mov_b32_e32 v95, v60
	v_mov_b32_e32 v60, v97
	s_waitcnt vmcnt(30)
	v_pk_fma_f32 v[2:3], v[202:203], v[2:3], v[78:79] op_sel_hi:[0,1,1]
	v_pk_fma_f32 v[20:21], v[202:203], v[30:31], v[20:21] op_sel_hi:[0,1,1]
	v_fmac_f32_e32 v71, v202, v47
	s_waitcnt vmcnt(29)
	v_pk_fma_f32 v[2:3], v[204:205], v[18:19], v[2:3] op_sel_hi:[0,1,1]
	v_pk_fma_f32 v[18:19], v[204:205], v[38:39], v[20:21] op_sel_hi:[0,1,1]
	v_fmac_f32_e32 v71, v204, v48
	s_waitcnt vmcnt(28)
	v_pk_fma_f32 v[2:3], v[206:207], v[4:5], v[2:3] op_sel_hi:[0,1,1]
	v_pk_fma_f32 v[4:5], v[206:207], v[32:33], v[18:19] op_sel_hi:[0,1,1]
	v_fmac_f32_e32 v71, v206, v49
	s_waitcnt vmcnt(27)
	v_pk_fma_f32 v[2:3], v[208:209], v[40:41], v[2:3] op_sel_hi:[0,1,1]
	v_pk_fma_f32 v[4:5], v[208:209], v[16:17], v[4:5] op_sel_hi:[0,1,1]
	v_fmac_f32_e32 v71, v208, v42
	s_waitcnt vmcnt(26)
	v_pk_fma_f32 v[2:3], v[210:211], v[22:23], v[2:3] op_sel_hi:[0,1,1]
	v_pk_fma_f32 v[4:5], v[210:211], v[26:27], v[4:5] op_sel_hi:[0,1,1]
	v_fmac_f32_e32 v71, v210, v43
	s_waitcnt vmcnt(25)
	v_pk_fma_f32 v[2:3], v[212:213], v[14:15], v[2:3] op_sel_hi:[0,1,1]
	v_pk_fma_f32 v[4:5], v[212:213], v[34:35], v[4:5] op_sel_hi:[0,1,1]
	v_fmac_f32_e32 v71, v212, v44
	s_waitcnt vmcnt(24)
	v_pk_fma_f32 v[2:3], v[214:215], v[24:25], v[2:3] op_sel_hi:[0,1,1]
	v_pk_fma_f32 v[4:5], v[214:215], v[28:29], v[4:5] op_sel_hi:[0,1,1]
	v_fmac_f32_e32 v71, v214, v45
	s_waitcnt vmcnt(23)
	v_pk_fma_f32 v[2:3], v[216:217], v[36:37], v[2:3] op_sel_hi:[0,1,1]
	v_pk_fma_f32 v[4:5], v[216:217], v[12:13], v[4:5] op_sel_hi:[0,1,1]
	s_waitcnt lgkmcnt(1)
	v_fmac_f32_e32 v71, v216, v102
	s_waitcnt vmcnt(22)
	v_pk_fma_f32 v[2:3], v[218:219], v[50:51], v[2:3] op_sel_hi:[0,1,1]
	v_pk_fma_f32 v[4:5], v[218:219], v[98:99], v[4:5] op_sel_hi:[0,1,1]
	v_fmac_f32_e32 v71, v218, v103
	s_waitcnt vmcnt(21)
	v_pk_fma_f32 v[2:3], v[220:221], v[10:11], v[2:3] op_sel_hi:[0,1,1]
	v_pk_fma_f32 v[4:5], v[220:221], v[90:91], v[4:5] op_sel_hi:[0,1,1]
	v_fmac_f32_e32 v71, v220, v104
	s_waitcnt vmcnt(20)
	v_pk_fma_f32 v[2:3], v[222:223], v[52:53], v[2:3] op_sel_hi:[0,1,1]
	v_pk_fma_f32 v[4:5], v[222:223], v[100:101], v[4:5] op_sel_hi:[0,1,1]
	v_fmac_f32_e32 v71, v222, v105
	s_waitcnt vmcnt(19)
	v_pk_fma_f32 v[2:3], v[224:225], v[92:93], v[2:3] op_sel_hi:[0,1,1]
	v_pk_fma_f32 v[4:5], v[224:225], v[8:9], v[4:5] op_sel_hi:[0,1,1]
	s_waitcnt lgkmcnt(0)
	v_fmac_f32_e32 v71, v224, v106
	s_waitcnt vmcnt(18)
	v_pk_fma_f32 v[2:3], v[226:227], v[54:55], v[2:3] op_sel_hi:[0,1,1]
	v_pk_fma_f32 v[4:5], v[226:227], v[58:59], v[4:5] op_sel_hi:[0,1,1]
	v_fmac_f32_e32 v71, v226, v107
	s_waitcnt vmcnt(17)
	v_pk_fma_f32 v[2:3], v[228:229], v[6:7], v[2:3] op_sel_hi:[0,1,1]
	v_pk_fma_f32 v[4:5], v[228:229], v[94:95], v[4:5] op_sel_hi:[0,1,1]
	v_fmac_f32_e32 v71, v228, v108
	v_add_u32_e32 v62, 64, v62
	s_waitcnt vmcnt(16)
	v_pk_fma_f32 v[78:79], v[230:231], v[56:57], v[2:3] op_sel_hi:[0,1,1]
	v_pk_fma_f32 v[80:81], v[230:231], v[60:61], v[4:5] op_sel_hi:[0,1,1]
	v_fmac_f32_e32 v71, v230, v109
	s_mov_b64 s[12:13], 0x120000
	v_lshl_add_u64 v[232:233], v[76:77], 0, s[12:13]
	global_load_dword v200, v[232:233], off
	v_lshl_add_u64 v[232:233], v[232:233], 0, s[38:39]
	global_load_dword v202, v[232:233], off
	v_lshl_add_u64 v[232:233], v[232:233], 0, s[38:39]
	global_load_dword v204, v[232:233], off
	v_lshl_add_u64 v[232:233], v[232:233], 0, s[38:39]
	global_load_dword v206, v[232:233], off
	v_lshl_add_u64 v[232:233], v[232:233], 0, s[38:39]
	global_load_dword v208, v[232:233], off
	v_lshl_add_u64 v[232:233], v[232:233], 0, s[38:39]
	global_load_dword v210, v[232:233], off
	v_lshl_add_u64 v[232:233], v[232:233], 0, s[38:39]
	global_load_dword v212, v[232:233], off
	v_lshl_add_u64 v[232:233], v[232:233], 0, s[38:39]
	global_load_dword v214, v[232:233], off
	v_lshl_add_u64 v[232:233], v[232:233], 0, s[38:39]
	global_load_dword v216, v[232:233], off
	v_lshl_add_u64 v[232:233], v[232:233], 0, s[38:39]
	global_load_dword v218, v[232:233], off
	v_lshl_add_u64 v[232:233], v[232:233], 0, s[38:39]
	global_load_dword v220, v[232:233], off
	v_lshl_add_u64 v[232:233], v[232:233], 0, s[38:39]
	global_load_dword v222, v[232:233], off
	v_lshl_add_u64 v[232:233], v[232:233], 0, s[38:39]
	global_load_dword v224, v[232:233], off
	v_lshl_add_u64 v[232:233], v[232:233], 0, s[38:39]
	global_load_dword v226, v[232:233], off
	v_lshl_add_u64 v[232:233], v[232:233], 0, s[38:39]
	global_load_dword v228, v[232:233], off
	v_lshl_add_u64 v[232:233], v[232:233], 0, s[38:39]
	global_load_dword v230, v[232:233], off
	ds_read_b128 v[18:21], v62
	ds_read_b128 v[14:17], v62 offset:16
	ds_read_b128 v[10:13], v62 offset:32
	ds_read_b128 v[6:9], v62 offset:48
	ds_read_b128 v[2:5], v62 offset:4096
	ds_read_b128 v[22:25], v62 offset:4112
	ds_read_b128 v[38:41], v62 offset:8192
	ds_read_b128 v[34:37], v62 offset:8208
	ds_read_b128 v[30:33], v62 offset:12288
	ds_read_b128 v[26:29], v62 offset:12304
	ds_read_b128 v[46:49], v62 offset:16384
	ds_read_b128 v[42:45], v62 offset:16400
	ds_read_b128 v[50:53], v62 offset:4128
	ds_read_b128 v[54:57], v62 offset:4144
	ds_read_b128 v[90:93], v62 offset:8224
	ds_read_b128 v[94:97], v62 offset:8240
	ds_read_b128 v[98:101], v62 offset:12320
	ds_read_b128 v[58:61], v62 offset:12336
	ds_read_b128 v[102:105], v62 offset:16416
	ds_read_b128 v[106:109], v62 offset:16432
	s_waitcnt lgkmcnt(14)
	v_mov_b32_e32 v140, v18
	v_mov_b32_e32 v141, v2
	v_mov_b32_e32 v2, v19
	v_mov_b32_e32 v18, v20
	v_mov_b32_e32 v19, v4
	v_mov_b32_e32 v4, v21
	s_waitcnt lgkmcnt(13)
	v_mov_b32_e32 v20, v38
	s_waitcnt lgkmcnt(11)
	v_mov_b32_e32 v21, v30
	v_mov_b32_e32 v30, v39
	v_mov_b32_e32 v38, v40
	v_mov_b32_e32 v39, v32
	v_mov_b32_e32 v32, v41
	v_mov_b32_e32 v40, v14
	v_mov_b32_e32 v41, v22
	v_mov_b32_e32 v22, v15
	v_mov_b32_e32 v14, v16
	v_mov_b32_e32 v15, v24
	v_mov_b32_e32 v24, v17
	v_mov_b32_e32 v16, v34
	s_waitcnt lgkmcnt(10)
	v_mov_b32_e32 v17, v26
	v_mov_b32_e32 v26, v35
	v_mov_b32_e32 v34, v36
	v_mov_b32_e32 v35, v28
	v_mov_b32_e32 v28, v37
	v_mov_b32_e32 v36, v10
	s_waitcnt lgkmcnt(7)
	v_mov_b32_e32 v37, v50
	v_mov_b32_e32 v50, v11
	v_mov_b32_e32 v10, v12
	v_mov_b32_e32 v11, v52
	v_mov_b32_e32 v52, v13
	s_waitcnt lgkmcnt(5)
	v_mov_b32_e32 v12, v90
	s_waitcnt lgkmcnt(3)
	v_mov_b32_e32 v13, v98
	v_mov_b32_e32 v98, v91
	v_mov_b32_e32 v90, v92
	v_mov_b32_e32 v91, v100
	v_mov_b32_e32 v100, v93
	v_mov_b32_e32 v92, v6
	v_mov_b32_e32 v93, v54
	s_waitcnt vmcnt(31)
	v_pk_fma_f32 v[78:79], v[110:111], v[140:141], v[78:79] op_sel_hi:[0,1,1]
	v_pk_fma_f32 v[20:21], v[110:111], v[20:21], v[80:81] op_sel_hi:[0,1,1]
	v_fmac_f32_e32 v71, v110, v46
	v_mov_b32_e32 v54, v7
	v_mov_b32_e32 v6, v8
	v_mov_b32_e32 v7, v56
	v_mov_b32_e32 v56, v9
	v_mov_b32_e32 v8, v94
	s_waitcnt lgkmcnt(2)
	v_mov_b32_e32 v9, v58
	v_mov_b32_e32 v58, v95
	v_mov_b32_e32 v94, v96
	v_mov_b32_e32 v95, v60
	v_mov_b32_e32 v60, v97
	s_waitcnt vmcnt(30)
	v_pk_fma_f32 v[2:3], v[112:113], v[2:3], v[78:79] op_sel_hi:[0,1,1]
	v_pk_fma_f32 v[20:21], v[112:113], v[30:31], v[20:21] op_sel_hi:[0,1,1]
	v_fmac_f32_e32 v71, v112, v47
	s_waitcnt vmcnt(29)
	v_pk_fma_f32 v[2:3], v[114:115], v[18:19], v[2:3] op_sel_hi:[0,1,1]
	v_pk_fma_f32 v[18:19], v[114:115], v[38:39], v[20:21] op_sel_hi:[0,1,1]
	v_fmac_f32_e32 v71, v114, v48
	s_waitcnt vmcnt(28)
	v_pk_fma_f32 v[2:3], v[116:117], v[4:5], v[2:3] op_sel_hi:[0,1,1]
	v_pk_fma_f32 v[4:5], v[116:117], v[32:33], v[18:19] op_sel_hi:[0,1,1]
	v_fmac_f32_e32 v71, v116, v49
	s_waitcnt vmcnt(27)
	v_pk_fma_f32 v[2:3], v[118:119], v[40:41], v[2:3] op_sel_hi:[0,1,1]
	v_pk_fma_f32 v[4:5], v[118:119], v[16:17], v[4:5] op_sel_hi:[0,1,1]
	v_fmac_f32_e32 v71, v118, v42
	s_waitcnt vmcnt(26)
	v_pk_fma_f32 v[2:3], v[120:121], v[22:23], v[2:3] op_sel_hi:[0,1,1]
	v_pk_fma_f32 v[4:5], v[120:121], v[26:27], v[4:5] op_sel_hi:[0,1,1]
	v_fmac_f32_e32 v71, v120, v43
	s_waitcnt vmcnt(25)
	v_pk_fma_f32 v[2:3], v[122:123], v[14:15], v[2:3] op_sel_hi:[0,1,1]
	v_pk_fma_f32 v[4:5], v[122:123], v[34:35], v[4:5] op_sel_hi:[0,1,1]
	v_fmac_f32_e32 v71, v122, v44
	s_waitcnt vmcnt(24)
	v_pk_fma_f32 v[2:3], v[124:125], v[24:25], v[2:3] op_sel_hi:[0,1,1]
	v_pk_fma_f32 v[4:5], v[124:125], v[28:29], v[4:5] op_sel_hi:[0,1,1]
	v_fmac_f32_e32 v71, v124, v45
	s_waitcnt vmcnt(23)
	v_pk_fma_f32 v[2:3], v[126:127], v[36:37], v[2:3] op_sel_hi:[0,1,1]
	v_pk_fma_f32 v[4:5], v[126:127], v[12:13], v[4:5] op_sel_hi:[0,1,1]
	s_waitcnt lgkmcnt(1)
	v_fmac_f32_e32 v71, v126, v102
	s_waitcnt vmcnt(22)
	v_pk_fma_f32 v[2:3], v[128:129], v[50:51], v[2:3] op_sel_hi:[0,1,1]
	v_pk_fma_f32 v[4:5], v[128:129], v[98:99], v[4:5] op_sel_hi:[0,1,1]
	v_fmac_f32_e32 v71, v128, v103
	s_waitcnt vmcnt(21)
	v_pk_fma_f32 v[2:3], v[130:131], v[10:11], v[2:3] op_sel_hi:[0,1,1]
	v_pk_fma_f32 v[4:5], v[130:131], v[90:91], v[4:5] op_sel_hi:[0,1,1]
	v_fmac_f32_e32 v71, v130, v104
	s_waitcnt vmcnt(20)
	v_pk_fma_f32 v[2:3], v[132:133], v[52:53], v[2:3] op_sel_hi:[0,1,1]
	v_pk_fma_f32 v[4:5], v[132:133], v[100:101], v[4:5] op_sel_hi:[0,1,1]
	v_fmac_f32_e32 v71, v132, v105
	s_waitcnt vmcnt(19)
	v_pk_fma_f32 v[2:3], v[134:135], v[92:93], v[2:3] op_sel_hi:[0,1,1]
	v_pk_fma_f32 v[4:5], v[134:135], v[8:9], v[4:5] op_sel_hi:[0,1,1]
	s_waitcnt lgkmcnt(0)
	v_fmac_f32_e32 v71, v134, v106
	s_waitcnt vmcnt(18)
	v_pk_fma_f32 v[2:3], v[136:137], v[54:55], v[2:3] op_sel_hi:[0,1,1]
	v_pk_fma_f32 v[4:5], v[136:137], v[58:59], v[4:5] op_sel_hi:[0,1,1]
	v_fmac_f32_e32 v71, v136, v107
	s_waitcnt vmcnt(17)
	v_pk_fma_f32 v[2:3], v[138:139], v[6:7], v[2:3] op_sel_hi:[0,1,1]
	v_pk_fma_f32 v[4:5], v[138:139], v[94:95], v[4:5] op_sel_hi:[0,1,1]
	v_fmac_f32_e32 v71, v138, v108
	v_add_u32_e32 v62, 64, v62
	s_waitcnt vmcnt(16)
	v_pk_fma_f32 v[78:79], v[82:83], v[56:57], v[2:3] op_sel_hi:[0,1,1]
	v_pk_fma_f32 v[80:81], v[82:83], v[60:61], v[4:5] op_sel_hi:[0,1,1]
	v_fmac_f32_e32 v71, v82, v109
	ds_read_b128 v[18:21], v62
	ds_read_b128 v[14:17], v62 offset:16
	ds_read_b128 v[10:13], v62 offset:32
	ds_read_b128 v[6:9], v62 offset:48
	ds_read_b128 v[2:5], v62 offset:4096
	ds_read_b128 v[22:25], v62 offset:4112
	ds_read_b128 v[38:41], v62 offset:8192
	ds_read_b128 v[34:37], v62 offset:8208
	ds_read_b128 v[30:33], v62 offset:12288
	ds_read_b128 v[26:29], v62 offset:12304
	ds_read_b128 v[46:49], v62 offset:16384
	ds_read_b128 v[42:45], v62 offset:16400
	ds_read_b128 v[50:53], v62 offset:4128
	ds_read_b128 v[54:57], v62 offset:4144
	ds_read_b128 v[90:93], v62 offset:8224
	ds_read_b128 v[94:97], v62 offset:8240
	ds_read_b128 v[98:101], v62 offset:12320
	ds_read_b128 v[58:61], v62 offset:12336
	ds_read_b128 v[102:105], v62 offset:16416
	ds_read_b128 v[106:109], v62 offset:16432
	s_waitcnt lgkmcnt(14)
	v_mov_b32_e32 v140, v18
	v_mov_b32_e32 v141, v2
	v_mov_b32_e32 v2, v19
	v_mov_b32_e32 v18, v20
	v_mov_b32_e32 v19, v4
	v_mov_b32_e32 v4, v21
	s_waitcnt lgkmcnt(13)
	v_mov_b32_e32 v20, v38
	s_waitcnt lgkmcnt(11)
	v_mov_b32_e32 v21, v30
	v_mov_b32_e32 v30, v39
	v_mov_b32_e32 v38, v40
	v_mov_b32_e32 v39, v32
	v_mov_b32_e32 v32, v41
	v_mov_b32_e32 v40, v14
	v_mov_b32_e32 v41, v22
	v_mov_b32_e32 v22, v15
	v_mov_b32_e32 v14, v16
	v_mov_b32_e32 v15, v24
	v_mov_b32_e32 v24, v17
	v_mov_b32_e32 v16, v34
	s_waitcnt lgkmcnt(10)
	v_mov_b32_e32 v17, v26
	v_mov_b32_e32 v26, v35
	v_mov_b32_e32 v34, v36
	v_mov_b32_e32 v35, v28
	v_mov_b32_e32 v28, v37
	v_mov_b32_e32 v36, v10
	s_waitcnt lgkmcnt(7)
	v_mov_b32_e32 v37, v50
	v_mov_b32_e32 v50, v11
	v_mov_b32_e32 v10, v12
	v_mov_b32_e32 v11, v52
	v_mov_b32_e32 v52, v13
	s_waitcnt lgkmcnt(5)
	v_mov_b32_e32 v12, v90
	s_waitcnt lgkmcnt(3)
	v_mov_b32_e32 v13, v98
	v_mov_b32_e32 v98, v91
	v_mov_b32_e32 v90, v92
	v_mov_b32_e32 v91, v100
	v_mov_b32_e32 v100, v93
	v_mov_b32_e32 v92, v6
	v_mov_b32_e32 v93, v54
	s_waitcnt vmcnt(15)
	v_pk_fma_f32 v[78:79], v[200:201], v[140:141], v[78:79] op_sel_hi:[0,1,1]
	v_pk_fma_f32 v[20:21], v[200:201], v[20:21], v[80:81] op_sel_hi:[0,1,1]
	v_fmac_f32_e32 v71, v200, v46
	v_mov_b32_e32 v54, v7
	v_mov_b32_e32 v6, v8
	v_mov_b32_e32 v7, v56
	v_mov_b32_e32 v56, v9
	v_mov_b32_e32 v8, v94
	s_waitcnt lgkmcnt(2)
	v_mov_b32_e32 v9, v58
	v_mov_b32_e32 v58, v95
	v_mov_b32_e32 v94, v96
	v_mov_b32_e32 v95, v60
	v_mov_b32_e32 v60, v97
	s_waitcnt vmcnt(14)
	v_pk_fma_f32 v[2:3], v[202:203], v[2:3], v[78:79] op_sel_hi:[0,1,1]
	v_pk_fma_f32 v[20:21], v[202:203], v[30:31], v[20:21] op_sel_hi:[0,1,1]
	v_fmac_f32_e32 v71, v202, v47
	s_waitcnt vmcnt(13)
	v_pk_fma_f32 v[2:3], v[204:205], v[18:19], v[2:3] op_sel_hi:[0,1,1]
	v_pk_fma_f32 v[18:19], v[204:205], v[38:39], v[20:21] op_sel_hi:[0,1,1]
	v_fmac_f32_e32 v71, v204, v48
	s_waitcnt vmcnt(12)
	v_pk_fma_f32 v[2:3], v[206:207], v[4:5], v[2:3] op_sel_hi:[0,1,1]
	v_pk_fma_f32 v[4:5], v[206:207], v[32:33], v[18:19] op_sel_hi:[0,1,1]
	v_fmac_f32_e32 v71, v206, v49
	s_waitcnt vmcnt(11)
	v_pk_fma_f32 v[2:3], v[208:209], v[40:41], v[2:3] op_sel_hi:[0,1,1]
	v_pk_fma_f32 v[4:5], v[208:209], v[16:17], v[4:5] op_sel_hi:[0,1,1]
	v_fmac_f32_e32 v71, v208, v42
	s_waitcnt vmcnt(10)
	v_pk_fma_f32 v[2:3], v[210:211], v[22:23], v[2:3] op_sel_hi:[0,1,1]
	v_pk_fma_f32 v[4:5], v[210:211], v[26:27], v[4:5] op_sel_hi:[0,1,1]
	v_fmac_f32_e32 v71, v210, v43
	s_waitcnt vmcnt(9)
	v_pk_fma_f32 v[2:3], v[212:213], v[14:15], v[2:3] op_sel_hi:[0,1,1]
	v_pk_fma_f32 v[4:5], v[212:213], v[34:35], v[4:5] op_sel_hi:[0,1,1]
	v_fmac_f32_e32 v71, v212, v44
	s_waitcnt vmcnt(8)
	v_pk_fma_f32 v[2:3], v[214:215], v[24:25], v[2:3] op_sel_hi:[0,1,1]
	v_pk_fma_f32 v[4:5], v[214:215], v[28:29], v[4:5] op_sel_hi:[0,1,1]
	v_fmac_f32_e32 v71, v214, v45
	s_waitcnt vmcnt(7)
	v_pk_fma_f32 v[2:3], v[216:217], v[36:37], v[2:3] op_sel_hi:[0,1,1]
	v_pk_fma_f32 v[4:5], v[216:217], v[12:13], v[4:5] op_sel_hi:[0,1,1]
	s_waitcnt lgkmcnt(1)
	v_fmac_f32_e32 v71, v216, v102
	s_waitcnt vmcnt(6)
	v_pk_fma_f32 v[2:3], v[218:219], v[50:51], v[2:3] op_sel_hi:[0,1,1]
	v_pk_fma_f32 v[4:5], v[218:219], v[98:99], v[4:5] op_sel_hi:[0,1,1]
	v_fmac_f32_e32 v71, v218, v103
	s_waitcnt vmcnt(5)
	v_pk_fma_f32 v[2:3], v[220:221], v[10:11], v[2:3] op_sel_hi:[0,1,1]
	v_pk_fma_f32 v[4:5], v[220:221], v[90:91], v[4:5] op_sel_hi:[0,1,1]
	v_fmac_f32_e32 v71, v220, v104
	s_waitcnt vmcnt(4)
	v_pk_fma_f32 v[2:3], v[222:223], v[52:53], v[2:3] op_sel_hi:[0,1,1]
	v_pk_fma_f32 v[4:5], v[222:223], v[100:101], v[4:5] op_sel_hi:[0,1,1]
	v_fmac_f32_e32 v71, v222, v105
	s_waitcnt vmcnt(3)
	v_pk_fma_f32 v[2:3], v[224:225], v[92:93], v[2:3] op_sel_hi:[0,1,1]
	v_pk_fma_f32 v[4:5], v[224:225], v[8:9], v[4:5] op_sel_hi:[0,1,1]
	s_waitcnt lgkmcnt(0)
	v_fmac_f32_e32 v71, v224, v106
	s_waitcnt vmcnt(2)
	v_pk_fma_f32 v[2:3], v[226:227], v[54:55], v[2:3] op_sel_hi:[0,1,1]
	v_pk_fma_f32 v[4:5], v[226:227], v[58:59], v[4:5] op_sel_hi:[0,1,1]
	v_fmac_f32_e32 v71, v226, v107
	s_waitcnt vmcnt(1)
	v_pk_fma_f32 v[2:3], v[228:229], v[6:7], v[2:3] op_sel_hi:[0,1,1]
	v_pk_fma_f32 v[4:5], v[228:229], v[94:95], v[4:5] op_sel_hi:[0,1,1]
	v_fmac_f32_e32 v71, v228, v108
	v_add_u32_e32 v62, 64, v62
	s_waitcnt vmcnt(0)
	v_pk_fma_f32 v[78:79], v[230:231], v[56:57], v[2:3] op_sel_hi:[0,1,1]
	v_pk_fma_f32 v[80:81], v[230:231], v[60:61], v[4:5] op_sel_hi:[0,1,1]
	v_fmac_f32_e32 v71, v230, v109
	s_movk_i32 s7, 0x280
	v_mul_lo_u32 v2, v72, s7
	v_lshlrev_b32_e32 v62, 2, v74
	v_add3_u32 v2, 0, v2, v62
	s_movk_i32 s7, 0xa0
	v_add_u32_e32 v3, 0x5000, v2
	v_cmp_gt_i32_e32 vcc, s7, v70
	ds_write2_b32 v3, v78, v79 offset1:32
	ds_write2_b32 v3, v80, v81 offset0:64 offset1:96
	ds_write_b32 v2, v71 offset:20992
	s_waitcnt lgkmcnt(0)
	s_barrier
	s_and_saveexec_b64 s[8:9], vcc
	s_cbranch_execz .LBB0_62
	s_load_dwordx16 s[72:87], s[0:1], 0x0
	s_mul_i32 s7, s6, 0x1800
	s_add_i32 s7, s7, s4
	v_or_b32_e32 v2, s7, v74
	v_ashrrev_i32_e32 v3, 31, v2
	s_waitcnt lgkmcnt(0)
	v_lshl_add_u64 v[2:3], v[2:3], 2, s[82:83]
	global_load_dword v22, v[2:3], off
	v_lshlrev_b32_e32 v4, 7, v72
	v_ashrrev_i32_e32 v73, 31, v72
	v_add3_u32 v6, 0, v62, v4
	v_mov_b64_e32 v[2:3], s[44:45]
	v_mad_i64_i32 v[4:5], s[6:7], s6, 5, v[72:73]
	v_add_u32_e32 v7, 0x5000, v6
	v_add_u32_e32 v8, 0x5400, v6
	v_add_u32_e32 v10, 0x5a00, v6
	v_add_u32_e32 v12, 0x5e00, v6
	v_add_u32_e32 v14, 0x6400, v6
	v_add_u32_e32 v16, 0x6800, v6
	v_add_u32_e32 v18, 0x6e00, v6
	v_add_u32_e32 v20, 0x7200, v6
	v_mad_u64_u32 v[2:3], s[6:7], v4, s63, v[2:3]
	ds_read2_b32 v[6:7], v7 offset1:160
	ds_read2_b32 v[8:9], v8 offset0:64 offset1:224
	ds_read2_b32 v[10:11], v10 offset1:160
	ds_read2_b32 v[12:13], v12 offset0:64 offset1:224
	ds_read2_b32 v[14:15], v14 offset1:160
	ds_read2_b32 v[16:17], v16 offset0:64 offset1:224
	ds_read2_b32 v[18:19], v18 offset1:160
	ds_read2_b32 v[20:21], v20 offset0:64 offset1:224
	s_waitcnt lgkmcnt(7)
	v_add_f32_e32 v4, 0, v6
	v_add_f32_e32 v4, v4, v7
	s_waitcnt lgkmcnt(6)
	v_add_f32_e32 v4, v4, v8
	v_add_f32_e32 v4, v4, v9
	s_waitcnt lgkmcnt(5)
	v_add_f32_e32 v4, v4, v10
	v_add_f32_e32 v4, v4, v11
	s_waitcnt lgkmcnt(4)
	v_add_f32_e32 v4, v4, v12
	v_add_f32_e32 v4, v4, v13
	s_waitcnt lgkmcnt(3)
	v_add_f32_e32 v4, v4, v14
	v_add_f32_e32 v4, v4, v15
	s_waitcnt lgkmcnt(2)
	v_add_f32_e32 v4, v4, v16
	v_add_f32_e32 v4, v4, v17
	s_waitcnt lgkmcnt(1)
	v_add_f32_e32 v4, v4, v18
	v_add_f32_e32 v4, v4, v19
	v_mad_i32_i24 v3, v5, s63, v3
	s_waitcnt lgkmcnt(0)
	v_add_f32_e32 v4, v4, v20
	v_lshl_add_u64 v[2:3], s[4:5], 2, v[2:3]
	v_add_f32_e32 v4, v4, v21
	v_lshl_add_u64 v[2:3], v[2:3], 0, v[62:63]
	s_waitcnt vmcnt(0)
	v_add_f32_e32 v4, v4, v22
	global_store_dword v[2:3], v4, off
	s_branch .LBB0_62
